# v34 + nt hint on the norm1 phase's streaming x/ctx loads
# baseline (speedup 1.0000x reference)
.LBB0_173:
	v_lshl_add_u64 v[30:31], s[20:21], 0, v[4:5]
	global_load_dwordx4 v[14:17], v[30:31], off nt
	global_load_dwordx4 v[18:21], v[30:31], off offset:1024 nt
	global_load_dwordx4 v[22:25], v[30:31], off offset:3072 nt
	global_load_dwordx4 v[26:29], v[30:31], off offset:2048 nt
	s_min_i32 s8, s16, 0x8000
	s_ashr_i32 s8, s8, 12
	s_mul_hi_i32 s21, s8, 0x6000
	s_mulk_i32 s8, 0x6000
	s_add_u32 s20, s12, s8
	s_addc_u32 s21, s13, s21
	v_lshl_add_u64 v[54:55], s[20:21], 0, v[4:5]
	v_add_co_u32_e32 v30, vcc, s3, v54
	v_lshl_add_u64 v[56:57], v[54:55], 0, s[14:15]
	s_nop 0
	v_addc_co_u32_e32 v31, vcc, 0, v55, vcc
	global_load_dwordx4 v[30:33], v[30:31], off nt
	s_nop 0
	global_load_dwordx4 v[34:37], v[56:57], off offset:1024 nt
	global_load_dwordx4 v[38:41], v[2:3], off offset:1024 nt
	global_load_dwordx4 v[42:45], v[2:3], off nt
	global_load_dwordx4 v[46:49], v[54:55], off offset:1024 nt
	global_load_dwordx4 v[50:53], v[54:55], off nt
	s_lshl_b64 s[16:17], s[16:17], 11
	s_add_i32 s23, s23, s24
	s_cmp_ge_i32 s23, s0
	s_waitcnt vmcnt(9)
	v_pk_mul_f32 v[58:59], v[16:17], v[16:17]
	v_pk_mul_f32 v[60:61], v[14:15], v[14:15]
	s_waitcnt vmcnt(8)
	v_pk_mul_f32 v[62:63], v[20:21], v[20:21]
	v_pk_mul_f32 v[64:65], v[18:19], v[18:19]
	v_pk_mov_b32 v[70:71], v[60:61], v[58:59] op_sel:[1,0]
	v_mov_b32_e32 v61, v59
	v_pk_mov_b32 v[58:59], v[64:65], v[62:63] op_sel:[1,0]
	v_mov_b32_e32 v65, v63
	s_waitcnt vmcnt(7)
	v_mul_f32_e32 v69, v23, v23
	s_waitcnt vmcnt(6)
	v_mul_f32_e32 v66, v27, v27
	v_mul_f32_e32 v68, v29, v29
	v_pk_add_f32 v[60:61], v[70:71], v[60:61]
	v_pk_add_f32 v[58:59], v[58:59], v[64:65]
	v_mul_f32_e32 v13, v22, v22
	v_mul_f32_e32 v72, v24, v24
	v_mul_f32_e32 v73, v25, v25
	v_pk_fma_f32 v[62:63], v[26:27], v[26:27], v[66:67] op_sel_hi:[1,1,0]
	v_pk_fma_f32 v[66:67], v[28:29], v[28:29], v[68:69] op_sel_hi:[1,1,0]
	v_pk_add_f32 v[60:61], v[60:61], v[60:61] op_sel:[0,1] op_sel_hi:[1,0]
	v_pk_add_f32 v[58:59], v[58:59], v[58:59] op_sel:[0,1] op_sel_hi:[1,0]
	v_mov_b32_e32 v63, v72
	v_mov_b32_e32 v67, v73
	v_mov_b32_e32 v61, v13
	v_mov_b32_e32 v59, v69
	v_pk_add_f32 v[62:63], v[62:63], v[66:67]
	v_pk_add_f32 v[58:59], v[60:61], v[58:59]
	s_waitcnt vmcnt(5)
	v_pk_add_f32 v[32:33], v[32:33], 1.0 op_sel_hi:[1,0]
	v_pk_add_f32 v[58:59], v[58:59], v[62:63]
	v_pk_add_f32 v[30:31], v[30:31], 1.0 op_sel_hi:[1,0]
	v_add_f32_e32 v13, v58, v59
	ds_bpermute_b32 v58, v6, v13
	s_waitcnt vmcnt(4)
	v_pk_add_f32 v[36:37], v[36:37], 1.0 op_sel_hi:[1,0]
	v_pk_add_f32 v[34:35], v[34:35], 1.0 op_sel_hi:[1,0]
	s_waitcnt lgkmcnt(0)
	v_add_f32_e32 v13, v13, v58
	ds_bpermute_b32 v58, v7, v13
	s_waitcnt lgkmcnt(0)
	v_add_f32_e32 v13, v13, v58
	ds_bpermute_b32 v58, v8, v13
	s_waitcnt lgkmcnt(0)
	v_add_f32_e32 v13, v13, v58
	ds_bpermute_b32 v58, v9, v13
	s_waitcnt lgkmcnt(0)
	v_add_f32_e32 v13, v13, v58
	ds_bpermute_b32 v58, v10, v13
	s_waitcnt lgkmcnt(0)
	v_add_f32_e32 v13, v13, v58
	ds_bpermute_b32 v60, v11, v13
	v_lshl_add_u64 v[58:59], v[0:1], 0, s[16:17]
	s_waitcnt lgkmcnt(0)
	v_add_f32_e32 v13, v13, v60
	v_fmamk_f32 v13, v13, 0x3a800000, v12
	v_mul_f32_e32 v60, 0x4b800000, v13
	v_cmp_gt_f32_e32 vcc, s1, v13
	s_nop 1
	v_cndmask_b32_e32 v13, v13, v60, vcc
	v_rsq_f32_e32 v13, v13
	s_nop 0
	v_mul_f32_e32 v60, 0x45800000, v13
	v_cndmask_b32_e32 v60, v13, v60, vcc
	v_pk_mul_f32 v[16:17], v[60:61], v[16:17] op_sel_hi:[0,1]
	v_pk_mul_f32 v[14:15], v[60:61], v[14:15] op_sel_hi:[0,1]
	v_pk_mul_f32 v[20:21], v[60:61], v[20:21] op_sel_hi:[0,1]
	v_pk_mul_f32 v[18:19], v[60:61], v[18:19] op_sel_hi:[0,1]
	s_waitcnt vmcnt(2)
	v_pk_mul_f32 v[14:15], v[42:43], v[14:15]
	v_pk_mul_f32 v[16:17], v[44:45], v[16:17]
	v_pk_mul_f32 v[18:19], v[38:39], v[18:19]
	v_pk_mul_f32 v[20:21], v[40:41], v[20:21]
	s_waitcnt vmcnt(0)
	v_pk_fma_f32 v[16:17], v[32:33], v[16:17], v[52:53]
	v_pk_fma_f32 v[14:15], v[30:31], v[14:15], v[50:51]
	v_pk_fma_f32 v[20:21], v[36:37], v[20:21], v[48:49]
	v_pk_fma_f32 v[18:19], v[34:35], v[18:19], v[46:47]
	v_cvt_pk_bf16_f32 v14, v14, v15
	v_cvt_pk_bf16_f32 v15, v16, v17
	v_cvt_pk_bf16_f32 v16, v18, v19
	v_cvt_pk_bf16_f32 v17, v20, v21
	global_store_dwordx2 v[58:59], v[14:15], off
	global_store_dwordx2 v[58:59], v[16:17], off offset:512
	global_load_dwordx4 v[14:17], v[56:57], off offset:2048 nt
	s_nop 0
	global_load_dwordx4 v[18:21], v[2:3], off offset:2048 nt
	global_load_dwordx4 v[30:33], v[56:57], off offset:3072 nt
	global_load_dwordx4 v[34:37], v[2:3], off offset:3072 nt
	global_load_dwordx4 v[38:41], v[54:55], off offset:2048 nt
	global_load_dwordx4 v[42:45], v[54:55], off offset:3072 nt
	v_pk_mul_f32 v[28:29], v[60:61], v[28:29] op_sel_hi:[0,1]
	v_pk_mul_f32 v[26:27], v[60:61], v[26:27] op_sel_hi:[0,1]
	v_pk_mul_f32 v[24:25], v[60:61], v[24:25] op_sel_hi:[0,1]
	v_pk_mul_f32 v[22:23], v[60:61], v[22:23] op_sel_hi:[0,1]
	s_waitcnt vmcnt(5)
	v_pk_add_f32 v[16:17], v[16:17], 1.0 op_sel_hi:[1,0]
	v_pk_add_f32 v[14:15], v[14:15], 1.0 op_sel_hi:[1,0]
	s_waitcnt vmcnt(4)
	v_pk_mul_f32 v[18:19], v[18:19], v[26:27]
	v_pk_mul_f32 v[20:21], v[20:21], v[28:29]
	s_waitcnt vmcnt(3)
	v_pk_add_f32 v[26:27], v[32:33], 1.0 op_sel_hi:[1,0]
	v_pk_add_f32 v[28:29], v[30:31], 1.0 op_sel_hi:[1,0]
	s_waitcnt vmcnt(2)
	v_pk_mul_f32 v[22:23], v[34:35], v[22:23]
	v_pk_mul_f32 v[24:25], v[36:37], v[24:25]
	s_waitcnt vmcnt(1)
	v_pk_fma_f32 v[16:17], v[16:17], v[20:21], v[40:41]
	v_pk_fma_f32 v[14:15], v[14:15], v[18:19], v[38:39]
	s_waitcnt vmcnt(0)
	v_pk_fma_f32 v[18:19], v[26:27], v[24:25], v[44:45]
	v_pk_fma_f32 v[20:21], v[28:29], v[22:23], v[42:43]
	v_cvt_pk_bf16_f32 v14, v14, v15
	v_cvt_pk_bf16_f32 v15, v16, v17
	v_cvt_pk_bf16_f32 v16, v20, v21
	v_cvt_pk_bf16_f32 v17, v18, v19
	global_store_dwordx2 v[58:59], v[14:15], off offset:1024
	global_store_dwordx2 v[58:59], v[16:17], off offset:1536
	s_cbranch_scc1 .LBB0_178

; __global__ void __launch_bounds__(NWAVES * 64, 2) fwd_kernel(Args args_unused) {
;     ...
;         { const bf16_t* Wgu = (const bf16_t*)(ws + WS_WGU); float* beta = (float*)(ws + WS_BETA);
;           f32x4 sh[8][4];
; #pragma unroll
;           for (int bb = 0; bb < 8; ++bb)
; #pragma unroll
;               for (int q = 0; q < 4; ++q) sh[bb][q] = *(const f32x4*)(mod + (size_t)bb * NMOD + 3 * DM + lane * 16 + 4 * q);
;           for (int it = gw; it < 2 * FFH; it += NGW) {
;               const u32x4 wa = *(const u32x4*)(Wgu + (size_t)it * DM + lane * 16), wb = *(const u32x4*)(Wgu + (size_t)it * DM + lane * 16 + 8);
;               f32x4 wf[4];
;               wf[0] = (f32x4){__uint_as_float(wa[0] << 16), __uint_as_float(wa[0] & 0xffff0000u), __uint_as_float(wa[1] << 16), __uint_as_float(wa[1] & 0xffff0000u)};
;               wf[1] = (f32x4){__uint_as_float(wa[2] << 16), __uint_as_float(wa[2] & 0xffff0000u), __uint_as_float(wa[3] << 16), __uint_as_float(wa[3] & 0xffff0000u)};
;               wf[2] = (f32x4){__uint_as_float(wb[0] << 16), __uint_as_float(wb[0] & 0xffff0000u), __uint_as_float(wb[1] << 16), __uint_as_float(wb[1] & 0xffff0000u)};
;               wf[3] = (f32x4){__uint_as_float(wb[2] << 16), __uint_as_float(wb[2] & 0xffff0000u), __uint_as_float(wb[3] << 16), __uint_as_float(wb[3] & 0xffff0000u)};
;               float a[8];
; #pragma unroll
;               for (int bb = 0; bb < 8; ++bb) { f32x4 t = sh[bb][0] * wf[0] + sh[bb][1] * wf[1] + sh[bb][2] * wf[2] + sh[bb][3] * wf[3]; a[bb] = (t[0] + t[1]) + (t[2] + t[3]); }
;               const bool c0 = lane & 1, c1 = lane & 2, c2 = lane & 4;
;               float p[4], q2[2], r1;
; #pragma unroll
;               for (int i = 0; i < 4; ++i) { const float keep = c0 ? a[i + 4] : a[i], send = c0 ? a[i] : a[i + 4]; p[i] = keep + __shfl_xor(send, 1); }
; #pragma unroll
;               for (int i = 0; i < 2; ++i) { const float keep = c1 ? p[i + 2] : p[i], send = c1 ? p[i] : p[i + 2]; q2[i] = keep + __shfl_xor(send, 2); }
;               { const float keep = c2 ? q2[1] : q2[0], send = c2 ? q2[0] : q2[1]; r1 = keep + __shfl_xor(send, 4); }
;               r1 += __shfl_xor(r1, 8); r1 += __shfl_xor(r1, 16); r1 += __shfl_xor(r1, 32);
;               if (lane < 8) { const int bb = 4 * (lane & 1) + 2 * ((lane >> 1) & 1) + ((lane >> 2) & 1); beta[(size_t)bb * (2 * FFH) + it] = r1; }
.LBB0_178:
	s_cmpk_lt_i32 s22, 0x1600
	s_cbranch_scc0 .LBB0_183
	v_lshlrev_b32_e32 v130, 4, v128
	v_ashrrev_i32_e32 v131, 31, v130
	v_lshl_add_u64 v[104:105], v[130:131], 2, s[12:13]
	v_add_co_u32_e32 v18, vcc, 0x2d000, v104
	s_mov_b64 s[0:1], 0x2d000
	s_nop 0
	v_addc_co_u32_e32 v19, vcc, 0, v105, vcc
	v_add_co_u32_e32 v34, vcc, 0x27000, v104
	v_lshl_add_u64 v[16:17], v[104:105], 0, s[0:1]
	s_nop 0
	v_addc_co_u32_e32 v35, vcc, 0, v105, vcc
	v_add_co_u32_e32 v50, vcc, 0x21000, v104
	s_mov_b64 s[0:1], 0x27000
	s_nop 0
	v_addc_co_u32_e32 v51, vcc, 0, v105, vcc
	v_add_co_u32_e32 v66, vcc, 0x1b000, v104
	v_lshl_add_u64 v[32:33], v[104:105], 0, s[0:1]
	s_nop 0
	v_addc_co_u32_e32 v67, vcc, 0, v105, vcc
	v_add_co_u32_e32 v82, vcc, 0x15000, v104
	s_mov_b64 s[0:1], 0x21000
	s_nop 0
	v_addc_co_u32_e32 v83, vcc, 0, v105, vcc
	v_lshl_add_u64 v[48:49], v[104:105], 0, s[0:1]
	s_mov_b64 s[0:1], 0x1b000
	v_add_co_u32_e32 v98, vcc, 0xf000, v104
	v_lshl_add_u64 v[64:65], v[104:105], 0, s[0:1]
	s_mov_b64 s[0:1], 0x15000
	v_addc_co_u32_e32 v99, vcc, 0, v105, vcc
	v_lshl_add_u64 v[80:81], v[104:105], 0, s[0:1]
	s_mov_b64 s[0:1], 0xf000
	v_add_co_u32_e32 v106, vcc, 0x9000, v104
	v_lshl_add_u64 v[96:97], v[104:105], 0, s[0:1]
	s_mov_b64 s[0:1], 0x9000
	v_addc_co_u32_e32 v107, vcc, 0, v105, vcc
	v_lshl_add_u64 v[116:117], v[104:105], 0, s[0:1]
	s_mov_b64 s[0:1], 0x3000
	v_add_co_u32_e32 v118, vcc, 0x3000, v104
	v_lshl_add_u64 v[124:125], v[104:105], 0, s[0:1]
	s_nop 0
	v_addc_co_u32_e32 v119, vcc, 0, v105, vcc
	global_load_dwordx4 v[0:3], v[18:19], off nt
	global_load_dwordx4 v[4:7], v[16:17], off offset:48 nt
	global_load_dwordx4 v[8:11], v[16:17], off offset:32 nt
	global_load_dwordx4 v[12:15], v[16:17], off offset:16 nt
	s_nop 0
	global_load_dwordx4 v[16:19], v[34:35], off nt
	global_load_dwordx4 v[20:23], v[32:33], off offset:48 nt
	global_load_dwordx4 v[24:27], v[32:33], off offset:32 nt
	global_load_dwordx4 v[28:31], v[32:33], off offset:16 nt
	s_nop 0
	global_load_dwordx4 v[32:35], v[50:51], off nt
	global_load_dwordx4 v[36:39], v[48:49], off offset:48 nt
	global_load_dwordx4 v[40:43], v[48:49], off offset:32 nt
	global_load_dwordx4 v[44:47], v[48:49], off offset:16 nt
	s_nop 0
	global_load_dwordx4 v[48:51], v[66:67], off nt
	global_load_dwordx4 v[52:55], v[64:65], off offset:48 nt
	global_load_dwordx4 v[56:59], v[64:65], off offset:32 nt
	global_load_dwordx4 v[60:63], v[64:65], off offset:16 nt
	s_nop 0
	global_load_dwordx4 v[64:67], v[82:83], off nt
	global_load_dwordx4 v[68:71], v[80:81], off offset:48 nt
	global_load_dwordx4 v[72:75], v[80:81], off offset:32 nt
	global_load_dwordx4 v[76:79], v[80:81], off offset:16 nt
	s_nop 0
	global_load_dwordx4 v[80:83], v[98:99], off nt
	global_load_dwordx4 v[84:87], v[96:97], off offset:48 nt
	global_load_dwordx4 v[88:91], v[96:97], off offset:32 nt
	global_load_dwordx4 v[92:95], v[96:97], off offset:16 nt
	s_nop 0
	global_load_dwordx4 v[96:99], v[106:107], off nt
	global_load_dwordx4 v[100:103], v[116:117], off offset:48 nt
	s_nop 0
	global_load_dwordx4 v[104:107], v[116:117], off offset:32 nt
	global_load_dwordx4 v[108:111], v[116:117], off offset:16 nt
	global_load_dwordx4 v[112:115], v[118:119], off nt
	s_nop 0
	global_load_dwordx4 v[116:119], v[124:125], off offset:48 nt
	global_load_dwordx4 v[120:123], v[124:125], off offset:32 nt
	s_nop 0
	global_load_dwordx4 v[124:127], v[124:125], off offset:16 nt
	v_and_b32_e32 v129, 1, v128
	v_cmp_eq_u32_e32 vcc, 0, v129
	v_and_b32_e32 v129, 2, v128
	v_cmp_eq_u32_e64 s[8:9], 0, v129
	v_and_b32_e32 v129, 4, v128
	v_cmp_eq_u32_e64 s[4:5], 0, v129
	v_mbcnt_lo_u32_b32 v129, -1, 0
	v_mbcnt_hi_u32_b32 v129, -1, v129
	v_and_b32_e32 v133, 64, v129
	v_xor_b32_e32 v132, 1, v129
	v_add_u32_e32 v133, 64, v133
	v_cmp_lt_i32_e64 s[6:7], v132, v133
	s_ashr_i32 s23, s22, 31
	s_lshl_b64 s[0:1], s[22:23], 2
	v_cndmask_b32_e64 v132, v129, v132, s[6:7]
	v_lshlrev_b32_e32 v148, 2, v132
	v_xor_b32_e32 v132, 2, v129
	v_cmp_lt_i32_e64 s[6:7], v132, v133
	s_add_u32 s0, s12, s0
	s_addc_u32 s1, s13, s1
	v_cndmask_b32_e64 v132, v129, v132, s[6:7]
	v_lshlrev_b32_e32 v149, 2, v132
	v_xor_b32_e32 v132, 4, v129
	v_cmp_lt_i32_e64 s[6:7], v132, v133
	s_movk_i32 s3, 0x5800
	s_ashr_i32 s25, s24, 31
	v_cndmask_b32_e64 v132, v129, v132, s[6:7]
	v_lshlrev_b32_e32 v150, 2, v132
	v_xor_b32_e32 v132, 8, v129
	v_cmp_lt_i32_e64 s[6:7], v132, v133
	s_lshl_b64 s[14:15], s[24:25], 2
	s_nop 0
	v_cndmask_b32_e64 v132, v129, v132, s[6:7]
	v_lshlrev_b32_e32 v151, 2, v132
	v_xor_b32_e32 v132, 16, v129
	v_cmp_lt_i32_e64 s[6:7], v132, v133
	s_nop 1
	v_cndmask_b32_e64 v132, v129, v132, s[6:7]
	v_lshlrev_b32_e32 v152, 2, v132
	v_xor_b32_e32 v132, 32, v129
	v_cmp_lt_i32_e64 s[6:7], v132, v133
	s_nop 1
	v_cndmask_b32_e64 v129, v129, v132, s[6:7]
	v_cmp_gt_i32_e64 s[6:7], 8, v128
	v_bfrev_b32_e32 v128, v128
	v_lshlrev_b32_e32 v153, 2, v129
	v_lshrrev_b32_e32 v132, 29, v128
	v_mov_b64_e32 v[128:129], s[0:1]
	v_mad_u64_u32 v[128:129], s[0:1], v132, s3, v[128:129]
	s_mov_b64 s[0:1], 0xc8000
	s_nop 0
	v_lshl_add_u64 v[128:129], v[128:129], 0, s[0:1]
	s_lshl_b64 s[0:1], s[22:23], 11
	s_add_u32 s0, s12, s0
	s_addc_u32 s1, s13, s1
	v_lshl_add_u64 v[130:131], v[130:131], 1, s[0:1]
	s_mov_b64 s[0:1], 0x900010
	v_lshl_add_u64 v[130:131], v[130:131], 0, s[0:1]
	s_lshl_b64 s[12:13], s[24:25], 11
	s_branch .LBB0_181

; __global__ void __launch_bounds__(NWAVES * 64, 2) fwd_kernel(Args args_unused) {
;     ...
;           for (int it = gw; it < 2 * FFH; it += NGW) {
;               const u32x4 wa = *(const u32x4*)(Wgu + (size_t)it * DM + lane * 16), wb = *(const u32x4*)(Wgu + (size_t)it * DM + lane * 16 + 8);
;               f32x4 wf[4];
;               wf[0] = (f32x4){__uint_as_float(wa[0] << 16), __uint_as_float(wa[0] & 0xffff0000u), __uint_as_float(wa[1] << 16), __uint_as_float(wa[1] & 0xffff0000u)};
;               wf[1] = (f32x4){__uint_as_float(wa[2] << 16), __uint_as_float(wa[2] & 0xffff0000u), __uint_as_float(wa[3] << 16), __uint_as_float(wa[3] & 0xffff0000u)};
;               wf[2] = (f32x4){__uint_as_float(wb[0] << 16), __uint_as_float(wb[0] & 0xffff0000u), __uint_as_float(wb[1] << 16), __uint_as_float(wb[1] & 0xffff0000u)};
;               wf[3] = (f32x4){__uint_as_float(wb[2] << 16), __uint_as_float(wb[2] & 0xffff0000u), __uint_as_float(wb[3] << 16), __uint_as_float(wb[3] & 0xffff0000u)};
;               float a[8];
; #pragma unroll
;               for (int bb = 0; bb < 8; ++bb) { f32x4 t = sh[bb][0] * wf[0] + sh[bb][1] * wf[1] + sh[bb][2] * wf[2] + sh[bb][3] * wf[3]; a[bb] = (t[0] + t[1]) + (t[2] + t[3]); }
;               const bool c0 = lane & 1, c1 = lane & 2, c2 = lane & 4;
;               float p[4], q2[2], r1;
; #pragma unroll
;               for (int i = 0; i < 4; ++i) { const float keep = c0 ? a[i + 4] : a[i], send = c0 ? a[i] : a[i + 4]; p[i] = keep + __shfl_xor(send, 1); }
; #pragma unroll
;               for (int i = 0; i < 2; ++i) { const float keep = c1 ? p[i + 2] : p[i], send = c1 ? p[i] : p[i + 2]; q2[i] = keep + __shfl_xor(send, 2); }
;               { const float keep = c2 ? q2[1] : q2[0], send = c2 ? q2[0] : q2[1]; r1 = keep + __shfl_xor(send, 4); }
;               r1 += __shfl_xor(r1, 8); r1 += __shfl_xor(r1, 16); r1 += __shfl_xor(r1, 32);
;               if (lane < 8) { const int bb = 4 * (lane & 1) + 2 * ((lane >> 1) & 1) + ((lane >> 2) & 1); beta[(size_t)bb * (2 * FFH) + it] = r1; }
.LBB0_181:
	global_load_dwordx4 v[134:137], v[130:131], off offset:-16 nt
	global_load_dwordx4 v[138:141], v[130:131], off nt
	s_waitcnt vmcnt(1)
	v_lshlrev_b32_e32 v146, 16, v136
	v_and_b32_e32 v147, 0xffff0000, v136
	v_lshlrev_b32_e32 v144, 16, v137
	v_and_b32_e32 v145, 0xffff0000, v137
	v_lshlrev_b32_e32 v132, 16, v134
	s_waitcnt lgkmcnt(0)
	v_and_b32_e32 v133, 0xffff0000, v134
	v_lshlrev_b32_e32 v134, 16, v135
	v_and_b32_e32 v135, 0xffff0000, v135
	v_pk_mul_f32 v[154:155], v[124:125], v[146:147]
	v_pk_mul_f32 v[156:157], v[126:127], v[144:145]
	s_waitcnt vmcnt(0)
	v_lshlrev_b32_e32 v142, 16, v138
	v_and_b32_e32 v143, 0xffff0000, v138
	v_lshlrev_b32_e32 v138, 16, v139
	v_and_b32_e32 v139, 0xffff0000, v139
	v_pk_mul_f32 v[158:159], v[108:109], v[146:147]
	v_pk_mul_f32 v[160:161], v[110:111], v[144:145]
	v_pk_mul_f32 v[162:163], v[92:93], v[146:147]
	v_pk_mul_f32 v[164:165], v[94:95], v[144:145]
	v_pk_mul_f32 v[166:167], v[76:77], v[146:147]
	v_pk_mul_f32 v[168:169], v[78:79], v[144:145]
	v_pk_mul_f32 v[170:171], v[60:61], v[146:147]
	v_pk_mul_f32 v[172:173], v[62:63], v[144:145]
	v_pk_fma_f32 v[156:157], v[114:115], v[134:135], v[156:157]
	v_pk_fma_f32 v[154:155], v[112:113], v[132:133], v[154:155]
	v_lshlrev_b32_e32 v136, 16, v140
	v_and_b32_e32 v137, 0xffff0000, v140
	v_lshlrev_b32_e32 v140, 16, v141
	v_and_b32_e32 v141, 0xffff0000, v141
	v_pk_fma_f32 v[160:161], v[98:99], v[134:135], v[160:161]
	v_pk_fma_f32 v[158:159], v[96:97], v[132:133], v[158:159]
	v_pk_fma_f32 v[164:165], v[82:83], v[134:135], v[164:165]
	v_pk_fma_f32 v[162:163], v[80:81], v[132:133], v[162:163]
	v_pk_fma_f32 v[168:169], v[66:67], v[134:135], v[168:169]
	v_pk_fma_f32 v[166:167], v[64:65], v[132:133], v[166:167]
	v_pk_fma_f32 v[172:173], v[50:51], v[134:135], v[172:173]
	v_pk_fma_f32 v[170:171], v[48:49], v[132:133], v[170:171]
	v_pk_fma_f32 v[154:155], v[120:121], v[142:143], v[154:155]
	v_pk_fma_f32 v[156:157], v[122:123], v[138:139], v[156:157]
	v_pk_fma_f32 v[158:159], v[104:105], v[142:143], v[158:159]
	v_pk_fma_f32 v[160:161], v[106:107], v[138:139], v[160:161]
	v_pk_fma_f32 v[162:163], v[88:89], v[142:143], v[162:163]
	v_pk_fma_f32 v[164:165], v[90:91], v[138:139], v[164:165]
	v_pk_fma_f32 v[166:167], v[72:73], v[142:143], v[166:167]
	v_pk_fma_f32 v[168:169], v[74:75], v[138:139], v[168:169]
	v_pk_fma_f32 v[170:171], v[56:57], v[142:143], v[170:171]
	v_pk_fma_f32 v[172:173], v[58:59], v[138:139], v[172:173]
	v_pk_fma_f32 v[156:157], v[118:119], v[140:141], v[156:157]
	v_pk_fma_f32 v[154:155], v[116:117], v[136:137], v[154:155]
	v_pk_mul_f32 v[174:175], v[44:45], v[146:147]
	v_pk_mul_f32 v[178:179], v[28:29], v[146:147]
	v_pk_fma_f32 v[160:161], v[102:103], v[140:141], v[160:161]
	v_pk_fma_f32 v[158:159], v[100:101], v[136:137], v[158:159]
	v_pk_fma_f32 v[164:165], v[86:87], v[140:141], v[164:165]
	v_pk_fma_f32 v[162:163], v[84:85], v[136:137], v[162:163]
	v_pk_fma_f32 v[168:169], v[70:71], v[140:141], v[168:169]
	v_pk_fma_f32 v[166:167], v[68:69], v[136:137], v[166:167]
	v_pk_fma_f32 v[172:173], v[54:55], v[140:141], v[172:173]
	v_pk_fma_f32 v[170:171], v[52:53], v[136:137], v[170:171]
	v_add_f32_e32 v154, v154, v155
	v_add_f32_e32 v155, v156, v157
	v_pk_mul_f32 v[146:147], v[12:13], v[146:147]
	v_pk_fma_f32 v[174:175], v[32:33], v[132:133], v[174:175]
	v_add_f32_e32 v156, v158, v159
	v_add_f32_e32 v157, v160, v161
	v_add_f32_e32 v158, v162, v163
	v_add_f32_e32 v159, v164, v165
	v_add_f32_e32 v160, v166, v167
	v_add_f32_e32 v161, v168, v169
	v_add_f32_e32 v162, v170, v171
	v_add_f32_e32 v163, v172, v173
	v_add_f32_e32 v166, v154, v155
	v_pk_fma_f32 v[154:155], v[16:17], v[132:133], v[178:179]
	v_pk_fma_f32 v[132:133], v[0:1], v[132:133], v[146:147]
	v_pk_mul_f32 v[176:177], v[46:47], v[144:145]
	v_pk_fma_f32 v[174:175], v[40:41], v[142:143], v[174:175]
	v_add_f32_e32 v158, v158, v159
	v_add_f32_e32 v159, v160, v161
	v_add_f32_e32 v160, v162, v163
	v_pk_fma_f32 v[154:155], v[24:25], v[142:143], v[154:155]
	v_pk_fma_f32 v[132:133], v[8:9], v[142:143], v[132:133]
	v_pk_mul_f32 v[180:181], v[30:31], v[144:145]
	v_pk_fma_f32 v[176:177], v[34:35], v[134:135], v[176:177]
	v_pk_fma_f32 v[174:175], v[36:37], v[136:137], v[174:175]
	v_pk_fma_f32 v[154:155], v[20:21], v[136:137], v[154:155]
	v_pk_mul_f32 v[144:145], v[14:15], v[144:145]
	v_pk_fma_f32 v[132:133], v[4:5], v[136:137], v[132:133]
	v_cndmask_b32_e32 v136, v166, v160, vcc
	v_pk_fma_f32 v[180:181], v[18:19], v[134:135], v[180:181]
	v_pk_fma_f32 v[176:177], v[42:43], v[138:139], v[176:177]
	v_pk_fma_f32 v[134:135], v[2:3], v[134:135], v[144:145]
	ds_bpermute_b32 v136, v148, v136
	v_pk_fma_f32 v[176:177], v[38:39], v[140:141], v[176:177]
	v_add_f32_e32 v167, v156, v157
	v_pk_fma_f32 v[156:157], v[26:27], v[138:139], v[180:181]
	v_pk_fma_f32 v[134:135], v[10:11], v[138:139], v[134:135]
	v_add_f32_e32 v164, v174, v175
	v_add_f32_e32 v165, v176, v177
	v_pk_fma_f32 v[156:157], v[22:23], v[140:141], v[156:157]
	v_pk_fma_f32 v[134:135], v[6:7], v[140:141], v[134:135]
	v_add_f32_e32 v161, v164, v165
	v_add_f32_e32 v154, v154, v155
	v_add_f32_e32 v155, v156, v157
	v_add_f32_e32 v132, v132, v133
	v_add_f32_e32 v133, v134, v135
	v_add_f32_e32 v154, v154, v155
	v_add_f32_e32 v132, v132, v133
	v_cndmask_b32_e32 v133, v160, v166, vcc
	v_cndmask_b32_e32 v135, v167, v161, vcc
	s_waitcnt lgkmcnt(0)
	v_add_f32_e32 v133, v133, v136
	ds_bpermute_b32 v135, v148, v135
	v_cndmask_b32_e32 v136, v158, v154, vcc
	v_cndmask_b32_e32 v137, v159, v132, vcc
	ds_bpermute_b32 v136, v148, v136
	ds_bpermute_b32 v137, v148, v137
	v_cndmask_b32_e32 v134, v161, v167, vcc
	s_waitcnt lgkmcnt(2)
	v_add_f32_e32 v134, v134, v135
	v_cndmask_b32_e32 v135, v154, v158, vcc
	v_cndmask_b32_e32 v132, v132, v159, vcc
	s_waitcnt lgkmcnt(1)
	v_add_f32_e32 v135, v135, v136
	s_waitcnt lgkmcnt(0)
	v_add_f32_e32 v132, v132, v137
	v_cndmask_b32_e64 v136, v133, v135, s[8:9]
	v_cndmask_b32_e64 v137, v134, v132, s[8:9]
	ds_bpermute_b32 v136, v149, v136
	ds_bpermute_b32 v137, v149, v137
	v_cndmask_b32_e64 v133, v135, v133, s[8:9]
	v_cndmask_b32_e64 v132, v132, v134, s[8:9]
	s_waitcnt lgkmcnt(1)
	v_add_f32_e32 v133, v133, v136
	s_waitcnt lgkmcnt(0)
	v_add_f32_e32 v132, v132, v137
	v_cndmask_b32_e64 v134, v133, v132, s[4:5]
	ds_bpermute_b32 v134, v150, v134
	v_cndmask_b32_e64 v132, v132, v133, s[4:5]
	s_waitcnt lgkmcnt(0)
	v_add_f32_e32 v132, v132, v134
	ds_bpermute_b32 v133, v151, v132
	s_waitcnt lgkmcnt(0)
	v_add_f32_e32 v132, v132, v133
	ds_bpermute_b32 v133, v152, v132
	s_waitcnt lgkmcnt(0)
	v_add_f32_e32 v132, v132, v133
	ds_bpermute_b32 v133, v153, v132
	s_and_saveexec_b64 s[16:17], s[6:7]
	s_cbranch_execz .LBB0_180
	s_waitcnt lgkmcnt(0)
	v_add_f32_e32 v132, v132, v133
	global_store_dword v[128:129], v132, off
	s_branch .LBB0_180
